# FFN_IN K-loops: SP2 load segments' six 64-bit DMA address adds precomputed inside the same wave's preceding MFMA block
# baseline (speedup 1.0000x reference)
; #define PG8_STAGE(bufoff, gbase, voff) do { _Pragma("unroll") for (int _i = 0; _i < 2; ++_i) \
;         __builtin_amdgcn_global_load_lds((const unsigned*)((const char*)(gbase) + (voff)[_i]), (PG8_LAS unsigned*)(lds + (bufoff) + ldsw + _i * 8192), 16, 0, 0); } while (0)
; #define PG8_LDA(dst, b, h) do { _Pragma("unroll") for (int m = 0; m < 4; ++m) _Pragma("unroll") for (int k = 0; k < 2; ++k) dst[m][k] = *(const PG8_LAS bf16x8*)(lds + PG8_SA(b, h) + aoff + m * 2048 + k * 1024); } while (0)
; #define PG8_LDB(dst, b, h) do { _Pragma("unroll") for (int n = 0; n < 2; ++n) _Pragma("unroll") for (int k = 0; k < 2; ++k) dst[n][k] = *(const PG8_LAS bf16x8*)(lds + PG8_SB(b, h) + boff + n * 2048 + k * 1024); } while (0)
; #define PG8_MMA(ai, bj, At, Bt) do { __builtin_amdgcn_s_setprio(1); _Pragma("unroll") for (int m = 0; m < 4; ++m) _Pragma("unroll") for (int n = 0; n < 2; ++n) _Pragma("unroll") for (int k = 0; k < 2; ++k) \
;         acc[ai][bj][m][n] = __builtin_amdgcn_mfma_f32_16x16x32_bf16(Bt[n][k], At[m][k], acc[ai][bj][m][n], 0, 0, 0); __builtin_amdgcn_s_setprio(0); } while (0)
; #define PG8_WAIT_V(n) asm volatile("s_waitcnt vmcnt(" #n ")" ::: "memory")
; #define PG8_WAIT_L(n) asm volatile("s_waitcnt lgkmcnt(" #n ")" ::: "memory")
; #define PG8_BAR __builtin_amdgcn_s_barrier()
; #define PG8_SCHED __builtin_amdgcn_sched_barrier(0)
; template <class Epi, class Sched, bool ALIGN_EPI = false, bool SP2 = false>
; __device__ __forceinline__ void gemm_phase(PG8_LAS unsigned char* lds, const Gemm g, const Sched& S, const Epi& E) {
;     ...
;             const bool last = (t == nt - 2);
;             const char* a1 = cA + (size_t)(t + 1) * kstep;
;             const char* a2 = last ? nA : cA + (size_t)(t + 2) * kstep; const char* b2 = last ? nB : cB + (size_t)(t + 2) * kstep;
;             const char* a3 = a2 + kstep; const char* b3 = b2 + kstep;
;             if (last && has_next) S.a_ready(nxt);
;             if constexpr (SP2) {
;             PG8_LDB(B0, 0, 0); PG8_LDB(B1, 0, 1); PG8_SCHED; PG8_LDA(At, 0, 0); PG8_STAGE(PG8_SA(1, 1), a1 + hstepA, voffA);
;             PG8_WAIT_V(8); PG8_WAIT_L(0); PG8_BAR; PG8_MMA(0, 0, At, B0); PG8_MMA(0, 1, At, B1); PG8_BAR; PG8_SCHED;
;             PG8_LDA(At, 0, 1); PG8_STAGE(PG8_SB(0, 0), b2, voffB); PG8_STAGE(PG8_SB(0, 1), b2 + hstepB, voffB); PG8_STAGE(PG8_SA(0, 0), a2, voffA);
.LBB0_736:
	ds_read_b128 v[144:147], v149
	ds_read_b128 v[154:157], v149 offset:1024
	ds_read_b128 v[158:161], v149 offset:2048
	ds_read_b128 v[162:165], v149 offset:3072
	ds_read_b128 v[168:171], v150
	ds_read_b128 v[172:175], v150 offset:1024
	ds_read_b128 v[176:179], v150 offset:2048
	ds_read_b128 v[180:183], v150 offset:3072
	s_add_u32 s4, s28, 0xfff80080
	s_addc_u32 s5, s29, -1
	s_cmp_eq_u32 s60, 28
	s_cselect_b32 s35, s19, s5
	s_cselect_b32 s34, s56, s4
	s_cselect_b32 s31, s17, s59
	s_cselect_b32 s30, s57, s58
	v_lshl_add_u64 v[216:217], s[28:29], 0, v[136:137]
	s_add_i32 m0, s27, 0xc000
	ds_read_b128 v[184:187], v151
	ds_read_b128 v[188:191], v151 offset:1024
	ds_read_b128 v[192:195], v151 offset:2048
	ds_read_b128 v[196:199], v151 offset:3072
	ds_read_b128 v[200:203], v151 offset:4096
	ds_read_b128 v[204:207], v151 offset:5120
	ds_read_b128 v[208:211], v151 offset:6144
	ds_read_b128 v[212:215], v151 offset:7168
	global_load_lds_dwordx4 v[216:217], off
	v_lshl_add_u64 v[216:217], s[28:29], 0, v[138:139]
	s_add_i32 m0, s27, 0xe000
	s_nop 0
	global_load_lds_dwordx4 v[216:217], off
	s_waitcnt vmcnt(8)
	s_waitcnt lgkmcnt(0)
	s_barrier
	s_setprio 1
	v_mfma_f32_16x16x32_bf16 v[116:119], v[144:147], v[184:187], v[116:119]
	s_add_u32 s100, s30, 0x80000
	s_addc_u32 s101, s31, 0
	v_mfma_f32_16x16x32_bf16 v[112:115], v[158:161], v[184:187], v[112:115]
	v_mfma_f32_16x16x32_bf16 v[100:103], v[144:147], v[192:195], v[100:103]
	v_lshl_add_u64 v[216:217], s[30:31], 0, v[132:133]
	v_mfma_f32_16x16x32_bf16 v[96:99], v[158:161], v[192:195], v[96:99]
	v_mfma_f32_16x16x32_bf16 v[84:87], v[144:147], v[200:203], v[84:87]
	v_mfma_f32_16x16x32_bf16 v[80:83], v[158:161], v[200:203], v[80:83]
	v_mfma_f32_16x16x32_bf16 v[68:71], v[144:147], v[208:211], v[68:71]
	v_lshl_add_u64 v[218:219], s[30:31], 0, v[128:129]
	v_mfma_f32_16x16x32_bf16 v[64:67], v[158:161], v[208:211], v[64:67]
	v_mfma_f32_16x16x32_bf16 v[116:119], v[154:157], v[188:191], v[116:119]
	v_mfma_f32_16x16x32_bf16 v[112:115], v[162:165], v[188:191], v[112:115]
	v_mfma_f32_16x16x32_bf16 v[100:103], v[154:157], v[196:199], v[100:103]
	v_lshl_add_u64 v[242:243], s[100:101], 0, v[132:133]
	v_mfma_f32_16x16x32_bf16 v[96:99], v[162:165], v[196:199], v[96:99]
	v_mfma_f32_16x16x32_bf16 v[84:87], v[154:157], v[204:207], v[84:87]
	v_mfma_f32_16x16x32_bf16 v[80:83], v[162:165], v[204:207], v[80:83]
	v_mfma_f32_16x16x32_bf16 v[68:71], v[154:157], v[212:215], v[68:71]
	v_mfma_f32_16x16x32_bf16 v[64:67], v[162:165], v[212:215], v[64:67]
	v_mfma_f32_16x16x32_bf16 v[124:127], v[168:171], v[184:187], v[124:127]
	v_mfma_f32_16x16x32_bf16 v[120:123], v[176:179], v[184:187], v[120:123]
	v_mfma_f32_16x16x32_bf16 v[108:111], v[168:171], v[192:195], v[108:111]
	v_lshl_add_u64 v[244:245], s[100:101], 0, v[128:129]
	v_mfma_f32_16x16x32_bf16 v[104:107], v[176:179], v[192:195], v[104:107]
	v_mfma_f32_16x16x32_bf16 v[92:95], v[168:171], v[200:203], v[92:95]
	v_mfma_f32_16x16x32_bf16 v[88:91], v[176:179], v[200:203], v[88:91]
	v_mfma_f32_16x16x32_bf16 v[76:79], v[168:171], v[208:211], v[76:79]
	v_lshl_add_u64 v[220:221], s[34:35], 0, v[134:135]
	v_mfma_f32_16x16x32_bf16 v[72:75], v[176:179], v[208:211], v[72:75]
	v_mfma_f32_16x16x32_bf16 v[124:127], v[172:175], v[188:191], v[124:127]
	v_mfma_f32_16x16x32_bf16 v[120:123], v[180:183], v[188:191], v[120:123]
	v_mfma_f32_16x16x32_bf16 v[108:111], v[172:175], v[196:199], v[108:111]
	v_lshl_add_u64 v[222:223], s[34:35], 0, v[130:131]
	v_mfma_f32_16x16x32_bf16 v[104:107], v[180:183], v[196:199], v[104:107]
	v_mfma_f32_16x16x32_bf16 v[92:95], v[172:175], v[204:207], v[92:95]
	v_mfma_f32_16x16x32_bf16 v[88:91], v[180:183], v[204:207], v[88:91]
	v_mfma_f32_16x16x32_bf16 v[76:79], v[172:175], v[212:215], v[76:79]
	v_mfma_f32_16x16x32_bf16 v[72:75], v[180:183], v[212:215], v[72:75]
	s_setprio 0
	s_barrier
	s_add_i32 s4, s41, s47
	s_mov_b32 m0, s4
	ds_read_b128 v[184:187], v151 offset:16384
	ds_read_b128 v[188:191], v151 offset:17408
	ds_read_b128 v[192:195], v151 offset:18432
	ds_read_b128 v[196:199], v151 offset:19456
	ds_read_b128 v[200:203], v151 offset:20480
	ds_read_b128 v[204:207], v151 offset:21504
	ds_read_b128 v[208:211], v151 offset:22528
	ds_read_b128 v[212:215], v151 offset:23552
	global_load_lds_dwordx4 v[216:217], off
	s_add_i32 m0, s4, 0x2000
	s_add_i32 s61, s44, s47
	global_load_lds_dwordx4 v[218:219], off
	s_mov_b32 m0, s61
	s_nop 0
	global_load_lds_dwordx4 v[242:243], off
	s_add_i32 m0, s61, 0x2000
	s_nop 0
	global_load_lds_dwordx4 v[244:245], off
	s_mov_b32 m0, s27
	s_nop 0
	global_load_lds_dwordx4 v[220:221], off
	s_mov_b32 m0, s33
	s_nop 0
	global_load_lds_dwordx4 v[222:223], off
	s_waitcnt vmcnt(8)
	s_waitcnt lgkmcnt(0)
	s_barrier
; #define PG8_STAGE(bufoff, gbase, voff) do { _Pragma("unroll") for (int _i = 0; _i < 2; ++_i) \
;         __builtin_amdgcn_global_load_lds((const unsigned*)((const char*)(gbase) + (voff)[_i]), (PG8_LAS unsigned*)(lds + (bufoff) + ldsw + _i * 8192), 16, 0, 0); } while (0)
; #define PG8_LDA(dst, b, h) do { _Pragma("unroll") for (int m = 0; m < 4; ++m) _Pragma("unroll") for (int k = 0; k < 2; ++k) dst[m][k] = *(const PG8_LAS bf16x8*)(lds + PG8_SA(b, h) + aoff + m * 2048 + k * 1024); } while (0)
; #define PG8_LDB(dst, b, h) do { _Pragma("unroll") for (int n = 0; n < 2; ++n) _Pragma("unroll") for (int k = 0; k < 2; ++k) dst[n][k] = *(const PG8_LAS bf16x8*)(lds + PG8_SB(b, h) + boff + n * 2048 + k * 1024); } while (0)
; #define PG8_MMA(ai, bj, At, Bt) do { __builtin_amdgcn_s_setprio(1); _Pragma("unroll") for (int m = 0; m < 4; ++m) _Pragma("unroll") for (int n = 0; n < 2; ++n) _Pragma("unroll") for (int k = 0; k < 2; ++k) \
;         acc[ai][bj][m][n] = __builtin_amdgcn_mfma_f32_16x16x32_bf16(Bt[n][k], At[m][k], acc[ai][bj][m][n], 0, 0, 0); __builtin_amdgcn_s_setprio(0); } while (0)
; #define PG8_WAIT_V(n) asm volatile("s_waitcnt vmcnt(" #n ")" ::: "memory")
; #define PG8_WAIT_L(n) asm volatile("s_waitcnt lgkmcnt(" #n ")" ::: "memory")
; #define PG8_BAR __builtin_amdgcn_s_barrier()
; #define PG8_SCHED __builtin_amdgcn_sched_barrier(0)
; template <class Epi, class Sched, bool ALIGN_EPI = false, bool SP2 = false>
; __device__ __forceinline__ void gemm_phase(PG8_LAS unsigned char* lds, const Gemm g, const Sched& S, const Epi& E) {
;     ...
;             PG8_WAIT_V(8); PG8_WAIT_L(0); PG8_BAR; PG8_MMA(1, 0, At, B0); PG8_MMA(1, 1, At, B1); PG8_BAR; PG8_SCHED;
;             PG8_LDB(B0, 1, 0); PG8_LDB(B1, 1, 1); PG8_SCHED; PG8_LDA(At, 1, 0); PG8_STAGE(PG8_SA(0, 1), a2 + hstepA, voffA);
	s_setprio 1
	v_mfma_f32_16x16x32_bf16 v[52:55], v[144:147], v[184:187], v[52:55]
	v_mfma_f32_16x16x32_bf16 v[48:51], v[158:161], v[184:187], v[48:51]
	v_mfma_f32_16x16x32_bf16 v[36:39], v[144:147], v[192:195], v[36:39]
	v_mfma_f32_16x16x32_bf16 v[32:35], v[158:161], v[192:195], v[32:35]
	v_mfma_f32_16x16x32_bf16 v[20:23], v[144:147], v[200:203], v[20:23]
	v_mfma_f32_16x16x32_bf16 v[16:19], v[158:161], v[200:203], v[16:19]
	v_mfma_f32_16x16x32_bf16 v[8:11], v[144:147], v[208:211], v[8:11]
	v_mfma_f32_16x16x32_bf16 v[4:7], v[158:161], v[208:211], v[4:7]
	v_mfma_f32_16x16x32_bf16 v[52:55], v[154:157], v[188:191], v[52:55]
	v_mfma_f32_16x16x32_bf16 v[48:51], v[162:165], v[188:191], v[48:51]
	v_mfma_f32_16x16x32_bf16 v[36:39], v[154:157], v[196:199], v[36:39]
	v_mfma_f32_16x16x32_bf16 v[32:35], v[162:165], v[196:199], v[32:35]
	v_mfma_f32_16x16x32_bf16 v[20:23], v[154:157], v[204:207], v[20:23]
	v_mfma_f32_16x16x32_bf16 v[16:19], v[162:165], v[204:207], v[16:19]
	v_mfma_f32_16x16x32_bf16 v[8:11], v[154:157], v[212:215], v[8:11]
	v_mfma_f32_16x16x32_bf16 v[4:7], v[162:165], v[212:215], v[4:7]
	v_mfma_f32_16x16x32_bf16 v[60:63], v[168:171], v[184:187], v[60:63]
	v_mfma_f32_16x16x32_bf16 v[56:59], v[176:179], v[184:187], v[56:59]
	v_mfma_f32_16x16x32_bf16 v[44:47], v[168:171], v[192:195], v[44:47]
	v_mfma_f32_16x16x32_bf16 v[40:43], v[176:179], v[192:195], v[40:43]
	v_mfma_f32_16x16x32_bf16 v[28:31], v[168:171], v[200:203], v[28:31]
	v_mfma_f32_16x16x32_bf16 v[24:27], v[176:179], v[200:203], v[24:27]
	v_mfma_f32_16x16x32_bf16 v[12:15], v[168:171], v[208:211], v[12:15]
	v_mfma_f32_16x16x32_bf16 v[0:3], v[176:179], v[208:211], v[0:3]
	v_mfma_f32_16x16x32_bf16 v[60:63], v[172:175], v[188:191], v[60:63]
	v_mfma_f32_16x16x32_bf16 v[56:59], v[180:183], v[188:191], v[56:59]
	v_mfma_f32_16x16x32_bf16 v[44:47], v[172:175], v[196:199], v[44:47]
	v_mfma_f32_16x16x32_bf16 v[40:43], v[180:183], v[196:199], v[40:43]
	v_mfma_f32_16x16x32_bf16 v[28:31], v[172:175], v[204:207], v[28:31]
	v_mfma_f32_16x16x32_bf16 v[24:27], v[180:183], v[204:207], v[24:27]
	v_mfma_f32_16x16x32_bf16 v[12:15], v[172:175], v[212:215], v[12:15]
	v_mfma_f32_16x16x32_bf16 v[0:3], v[180:183], v[212:215], v[0:3]
	s_setprio 0
	s_barrier
	s_add_i32 s61, 0, 0x18000
	v_add_u32_e32 v153, s61, v148
	s_add_i32 s62, 0, 0x1c000
	ds_read_b128 v[144:147], v153
	ds_read_b128 v[154:157], v153 offset:1024
	ds_read_b128 v[158:161], v153 offset:2048
	ds_read_b128 v[162:165], v153 offset:3072
	v_add_u32_e32 v153, s62, v148
	ds_read_b128 v[168:171], v153
	ds_read_b128 v[172:175], v153 offset:1024
	ds_read_b128 v[176:179], v153 offset:2048
	ds_read_b128 v[180:183], v153 offset:3072
	s_add_u32 s4, s34, 0x80000
	s_addc_u32 s5, s35, 0
	s_mov_b32 m0, s36
	v_lshl_add_u64 v[224:225], s[4:5], 0, v[134:135]
	ds_read_b128 v[184:187], v151 offset:32768
	ds_read_b128 v[188:191], v151 offset:33792
	ds_read_b128 v[192:195], v151 offset:34816
	ds_read_b128 v[196:199], v151 offset:35840
	ds_read_b128 v[200:203], v151 offset:36864
	ds_read_b128 v[204:207], v151 offset:37888
	ds_read_b128 v[208:211], v151 offset:38912
	ds_read_b128 v[212:215], v151 offset:39936
	global_load_lds_dwordx4 v[224:225], off
	v_lshl_add_u64 v[224:225], s[4:5], 0, v[130:131]
	s_mov_b32 m0, s37
	s_nop 0
	global_load_lds_dwordx4 v[224:225], off
	s_waitcnt vmcnt(8)
	s_waitcnt lgkmcnt(0)
	s_barrier
; #define PG8_STAGE(bufoff, gbase, voff) do { _Pragma("unroll") for (int _i = 0; _i < 2; ++_i) \
;         __builtin_amdgcn_global_load_lds((const unsigned*)((const char*)(gbase) + (voff)[_i]), (PG8_LAS unsigned*)(lds + (bufoff) + ldsw + _i * 8192), 16, 0, 0); } while (0)
; #define PG8_LDA(dst, b, h) do { _Pragma("unroll") for (int m = 0; m < 4; ++m) _Pragma("unroll") for (int k = 0; k < 2; ++k) dst[m][k] = *(const PG8_LAS bf16x8*)(lds + PG8_SA(b, h) + aoff + m * 2048 + k * 1024); } while (0)
; #define PG8_MMA(ai, bj, At, Bt) do { __builtin_amdgcn_s_setprio(1); _Pragma("unroll") for (int m = 0; m < 4; ++m) _Pragma("unroll") for (int n = 0; n < 2; ++n) _Pragma("unroll") for (int k = 0; k < 2; ++k) \
;         acc[ai][bj][m][n] = __builtin_amdgcn_mfma_f32_16x16x32_bf16(Bt[n][k], At[m][k], acc[ai][bj][m][n], 0, 0, 0); __builtin_amdgcn_s_setprio(0); } while (0)
; #define PG8_WAIT_V(n) asm volatile("s_waitcnt vmcnt(" #n ")" ::: "memory")
; #define PG8_WAIT_L(n) asm volatile("s_waitcnt lgkmcnt(" #n ")" ::: "memory")
; #define PG8_BAR __builtin_amdgcn_s_barrier()
; #define PG8_SCHED __builtin_amdgcn_sched_barrier(0)
; template <class Epi, class Sched, bool ALIGN_EPI = false, bool SP2 = false>
; __device__ __forceinline__ void gemm_phase(PG8_LAS unsigned char* lds, const Gemm g, const Sched& S, const Epi& E) {
;     ...
;             PG8_WAIT_V(8); PG8_WAIT_L(0); PG8_BAR; PG8_MMA(0, 0, At, B0); PG8_MMA(0, 1, At, B1); PG8_BAR; PG8_SCHED;
;             PG8_LDA(At, 1, 1); PG8_STAGE(PG8_SB(1, 0), b3, voffB); PG8_STAGE(PG8_SB(1, 1), b3 + hstepB, voffB); PG8_STAGE(PG8_SA(1, 0), a3, voffA);
;             PG8_WAIT_V(8); PG8_WAIT_L(0); PG8_BAR; PG8_MMA(1, 0, At, B0); PG8_MMA(1, 1, At, B1); PG8_BAR; PG8_SCHED;
	s_setprio 1
	v_mfma_f32_16x16x32_bf16 v[116:119], v[144:147], v[184:187], v[116:119]
	s_add_u32 s100, s30, 0x80080
	s_addc_u32 s101, s31, 0
	v_mfma_f32_16x16x32_bf16 v[112:115], v[158:161], v[184:187], v[112:115]
	v_mfma_f32_16x16x32_bf16 v[100:103], v[144:147], v[192:195], v[100:103]
	v_lshl_add_u64 v[216:217], v[216:217], 0, s[14:15]
	v_mfma_f32_16x16x32_bf16 v[96:99], v[158:161], v[192:195], v[96:99]
	v_mfma_f32_16x16x32_bf16 v[84:87], v[144:147], v[200:203], v[84:87]
	v_mfma_f32_16x16x32_bf16 v[80:83], v[158:161], v[200:203], v[80:83]
	v_mfma_f32_16x16x32_bf16 v[68:71], v[144:147], v[208:211], v[68:71]
	v_lshl_add_u64 v[218:219], v[218:219], 0, s[14:15]
	v_mfma_f32_16x16x32_bf16 v[64:67], v[158:161], v[208:211], v[64:67]
	v_mfma_f32_16x16x32_bf16 v[116:119], v[154:157], v[188:191], v[116:119]
	v_mfma_f32_16x16x32_bf16 v[112:115], v[162:165], v[188:191], v[112:115]
	v_mfma_f32_16x16x32_bf16 v[100:103], v[154:157], v[196:199], v[100:103]
	v_lshl_add_u64 v[242:243], s[100:101], 0, v[132:133]
	v_mfma_f32_16x16x32_bf16 v[96:99], v[162:165], v[196:199], v[96:99]
	v_mfma_f32_16x16x32_bf16 v[84:87], v[154:157], v[204:207], v[84:87]
	v_mfma_f32_16x16x32_bf16 v[80:83], v[162:165], v[204:207], v[80:83]
	v_mfma_f32_16x16x32_bf16 v[68:71], v[154:157], v[212:215], v[68:71]
	v_mfma_f32_16x16x32_bf16 v[64:67], v[162:165], v[212:215], v[64:67]
	v_mfma_f32_16x16x32_bf16 v[124:127], v[168:171], v[184:187], v[124:127]
	v_mfma_f32_16x16x32_bf16 v[120:123], v[176:179], v[184:187], v[120:123]
	v_mfma_f32_16x16x32_bf16 v[108:111], v[168:171], v[192:195], v[108:111]
	v_lshl_add_u64 v[244:245], s[100:101], 0, v[128:129]
	v_mfma_f32_16x16x32_bf16 v[104:107], v[176:179], v[192:195], v[104:107]
	v_mfma_f32_16x16x32_bf16 v[92:95], v[168:171], v[200:203], v[92:95]
	v_mfma_f32_16x16x32_bf16 v[88:91], v[176:179], v[200:203], v[88:91]
	v_mfma_f32_16x16x32_bf16 v[76:79], v[168:171], v[208:211], v[76:79]
	v_lshl_add_u64 v[220:221], v[220:221], 0, s[14:15]
	v_mfma_f32_16x16x32_bf16 v[72:75], v[176:179], v[208:211], v[72:75]
	v_mfma_f32_16x16x32_bf16 v[124:127], v[172:175], v[188:191], v[124:127]
	v_mfma_f32_16x16x32_bf16 v[120:123], v[180:183], v[188:191], v[120:123]
	v_mfma_f32_16x16x32_bf16 v[108:111], v[172:175], v[196:199], v[108:111]
	v_lshl_add_u64 v[222:223], v[222:223], 0, s[14:15]
	v_mfma_f32_16x16x32_bf16 v[104:107], v[180:183], v[196:199], v[104:107]
	v_mfma_f32_16x16x32_bf16 v[92:95], v[172:175], v[204:207], v[92:95]
	v_mfma_f32_16x16x32_bf16 v[88:91], v[180:183], v[204:207], v[88:91]
	v_mfma_f32_16x16x32_bf16 v[76:79], v[172:175], v[212:215], v[76:79]
	v_mfma_f32_16x16x32_bf16 v[72:75], v[180:183], v[212:215], v[72:75]
	s_setprio 0
	s_barrier
	s_add_i32 s4, s61, s47
	s_mov_b32 m0, s4
	ds_read_b128 v[184:187], v151 offset:49152
	ds_read_b128 v[188:191], v151 offset:50176
	ds_read_b128 v[192:195], v151 offset:51200
	ds_read_b128 v[196:199], v151 offset:52224
	ds_read_b128 v[200:203], v151 offset:53248
	ds_read_b128 v[204:207], v151 offset:54272
	ds_read_b128 v[208:211], v151 offset:55296
	ds_read_b128 v[212:215], v151 offset:56320
	global_load_lds_dwordx4 v[216:217], off
	s_add_i32 m0, s4, 0x2000
	s_add_i32 s30, s62, s47
	global_load_lds_dwordx4 v[218:219], off
	s_mov_b32 m0, s30
	s_nop 0
	global_load_lds_dwordx4 v[242:243], off
	s_add_i32 m0, s30, 0x2000
	s_nop 0
	global_load_lds_dwordx4 v[244:245], off
	s_mov_b32 m0, s39
	s_nop 0
	global_load_lds_dwordx4 v[220:221], off
	s_mov_b32 m0, s40
	s_nop 0
	global_load_lds_dwordx4 v[222:223], off
	s_waitcnt vmcnt(8)
	s_waitcnt lgkmcnt(0)
	s_barrier
	s_setprio 1
	v_mfma_f32_16x16x32_bf16 v[52:55], v[144:147], v[184:187], v[52:55]
	v_mfma_f32_16x16x32_bf16 v[48:51], v[158:161], v[184:187], v[48:51]
	v_mfma_f32_16x16x32_bf16 v[36:39], v[144:147], v[192:195], v[36:39]
	v_mfma_f32_16x16x32_bf16 v[32:35], v[158:161], v[192:195], v[32:35]
	v_mfma_f32_16x16x32_bf16 v[20:23], v[144:147], v[200:203], v[20:23]
	v_mfma_f32_16x16x32_bf16 v[16:19], v[158:161], v[200:203], v[16:19]
	v_mfma_f32_16x16x32_bf16 v[8:11], v[144:147], v[208:211], v[8:11]
	v_mfma_f32_16x16x32_bf16 v[4:7], v[158:161], v[208:211], v[4:7]
	v_mfma_f32_16x16x32_bf16 v[52:55], v[154:157], v[188:191], v[52:55]
	v_mfma_f32_16x16x32_bf16 v[48:51], v[162:165], v[188:191], v[48:51]
	v_mfma_f32_16x16x32_bf16 v[36:39], v[154:157], v[196:199], v[36:39]
	v_mfma_f32_16x16x32_bf16 v[32:35], v[162:165], v[196:199], v[32:35]
	v_mfma_f32_16x16x32_bf16 v[20:23], v[154:157], v[204:207], v[20:23]
	v_mfma_f32_16x16x32_bf16 v[16:19], v[162:165], v[204:207], v[16:19]
	v_mfma_f32_16x16x32_bf16 v[8:11], v[154:157], v[212:215], v[8:11]
	v_mfma_f32_16x16x32_bf16 v[4:7], v[162:165], v[212:215], v[4:7]
	v_mfma_f32_16x16x32_bf16 v[60:63], v[168:171], v[184:187], v[60:63]
	v_mfma_f32_16x16x32_bf16 v[56:59], v[176:179], v[184:187], v[56:59]
	v_mfma_f32_16x16x32_bf16 v[44:47], v[168:171], v[192:195], v[44:47]
	v_mfma_f32_16x16x32_bf16 v[40:43], v[176:179], v[192:195], v[40:43]
	v_mfma_f32_16x16x32_bf16 v[28:31], v[168:171], v[200:203], v[28:31]
	v_mfma_f32_16x16x32_bf16 v[24:27], v[176:179], v[200:203], v[24:27]
	v_mfma_f32_16x16x32_bf16 v[12:15], v[168:171], v[208:211], v[12:15]
	v_mfma_f32_16x16x32_bf16 v[0:3], v[176:179], v[208:211], v[0:3]
	v_mfma_f32_16x16x32_bf16 v[60:63], v[172:175], v[188:191], v[60:63]
	v_mfma_f32_16x16x32_bf16 v[56:59], v[180:183], v[188:191], v[56:59]
	v_mfma_f32_16x16x32_bf16 v[44:47], v[172:175], v[196:199], v[44:47]
	v_mfma_f32_16x16x32_bf16 v[40:43], v[180:183], v[196:199], v[40:43]
	v_mfma_f32_16x16x32_bf16 v[28:31], v[172:175], v[204:207], v[28:31]
	v_mfma_f32_16x16x32_bf16 v[24:27], v[180:183], v[204:207], v[24:27]
	v_mfma_f32_16x16x32_bf16 v[12:15], v[172:175], v[212:215], v[12:15]
	v_mfma_f32_16x16x32_bf16 v[0:3], v[180:183], v[212:215], v[0:3]
	s_setprio 0
	s_barrier
	s_add_i32 s60, s60, 2
	s_add_u32 s28, s28, 0x100
	s_addc_u32 s29, s29, 0
	s_add_u32 s58, s58, 0x100
	s_addc_u32 s59, s59, 0
	s_cmp_gt_u32 s60, 29
	s_cbranch_scc0 .LBB0_736
	s_and_b64 vcc, exec, s[48:49]
	s_cbranch_vccz .LBB0_739
	s_barrier

; #define PG8_STAGE(bufoff, gbase, voff) do { _Pragma("unroll") for (int _i = 0; _i < 2; ++_i) \
;         __builtin_amdgcn_global_load_lds((const unsigned*)((const char*)(gbase) + (voff)[_i]), (PG8_LAS unsigned*)(lds + (bufoff) + ldsw + _i * 8192), 16, 0, 0); } while (0)
; #define PG8_LDA(dst, b, h) do { _Pragma("unroll") for (int m = 0; m < 4; ++m) _Pragma("unroll") for (int k = 0; k < 2; ++k) dst[m][k] = *(const PG8_LAS bf16x8*)(lds + PG8_SA(b, h) + aoff + m * 2048 + k * 1024); } while (0)
; #define PG8_LDB(dst, b, h) do { _Pragma("unroll") for (int n = 0; n < 2; ++n) _Pragma("unroll") for (int k = 0; k < 2; ++k) dst[n][k] = *(const PG8_LAS bf16x8*)(lds + PG8_SB(b, h) + boff + n * 2048 + k * 1024); } while (0)
; #define PG8_MMA(ai, bj, At, Bt) do { __builtin_amdgcn_s_setprio(1); _Pragma("unroll") for (int m = 0; m < 4; ++m) _Pragma("unroll") for (int n = 0; n < 2; ++n) _Pragma("unroll") for (int k = 0; k < 2; ++k) \
;         acc[ai][bj][m][n] = __builtin_amdgcn_mfma_f32_16x16x32_bf16(Bt[n][k], At[m][k], acc[ai][bj][m][n], 0, 0, 0); __builtin_amdgcn_s_setprio(0); } while (0)
; #define PG8_WAIT_V(n) asm volatile("s_waitcnt vmcnt(" #n ")" ::: "memory")
; #define PG8_WAIT_L(n) asm volatile("s_waitcnt lgkmcnt(" #n ")" ::: "memory")
; #define PG8_BAR __builtin_amdgcn_s_barrier()
; #define PG8_SCHED __builtin_amdgcn_sched_barrier(0)
; template <class Epi, class Sched, bool ALIGN_EPI = false, bool SP2 = false>
; __device__ __forceinline__ void gemm_phase(PG8_LAS unsigned char* lds, const Gemm g, const Sched& S, const Epi& E) {
;     ...
;             const bool last = (t == nt - 2);
;             const char* a1 = cA + (size_t)(t + 1) * kstep;
;             const char* a2 = last ? nA : cA + (size_t)(t + 2) * kstep; const char* b2 = last ? nB : cB + (size_t)(t + 2) * kstep;
;             const char* a3 = a2 + kstep; const char* b3 = b2 + kstep;
;             if (last && has_next) S.a_ready(nxt);
;             if constexpr (SP2) {
;             PG8_LDB(B0, 0, 0); PG8_LDB(B1, 0, 1); PG8_SCHED; PG8_LDA(At, 0, 0); PG8_STAGE(PG8_SA(1, 1), a1 + hstepA, voffA);
;             PG8_WAIT_V(8); PG8_WAIT_L(0); PG8_BAR; PG8_MMA(0, 0, At, B0); PG8_MMA(0, 1, At, B1); PG8_BAR; PG8_SCHED;
;             PG8_LDA(At, 0, 1); PG8_STAGE(PG8_SB(0, 0), b2, voffB); PG8_STAGE(PG8_SB(0, 1), b2 + hstepB, voffB); PG8_STAGE(PG8_SA(0, 0), a2, voffA);
.LBB0_1287:
	ds_read_b128 v[144:147], v149
	ds_read_b128 v[154:157], v149 offset:1024
	ds_read_b128 v[158:161], v149 offset:2048
	ds_read_b128 v[162:165], v149 offset:3072
	ds_read_b128 v[168:171], v150
	ds_read_b128 v[172:175], v150 offset:1024
	ds_read_b128 v[176:179], v150 offset:2048
	ds_read_b128 v[180:183], v150 offset:3072
	s_add_u32 s4, s28, 0xfff80080
	s_addc_u32 s5, s29, -1
	s_cmp_eq_u32 s58, 28
	s_cselect_b32 s35, s19, s5
	s_cselect_b32 s34, s54, s4
	s_cselect_b32 s31, s17, s57
	s_cselect_b32 s30, s55, s56
	v_lshl_add_u64 v[216:217], s[28:29], 0, v[136:137]
	s_add_i32 m0, s27, 0xc000
	ds_read_b128 v[184:187], v151
	ds_read_b128 v[188:191], v151 offset:1024
	ds_read_b128 v[192:195], v151 offset:2048
	ds_read_b128 v[196:199], v151 offset:3072
	ds_read_b128 v[200:203], v151 offset:4096
	ds_read_b128 v[204:207], v151 offset:5120
	ds_read_b128 v[208:211], v151 offset:6144
	ds_read_b128 v[212:215], v151 offset:7168
	global_load_lds_dwordx4 v[216:217], off
	v_lshl_add_u64 v[216:217], s[28:29], 0, v[138:139]
	s_add_i32 m0, s27, 0xe000
	s_nop 0
	global_load_lds_dwordx4 v[216:217], off
	s_waitcnt vmcnt(8)
	s_waitcnt lgkmcnt(0)
	s_barrier
	s_setprio 1
	v_mfma_f32_16x16x32_bf16 v[116:119], v[144:147], v[184:187], v[116:119]
	s_add_u32 s100, s30, 0x80000
	s_addc_u32 s101, s31, 0
	v_mfma_f32_16x16x32_bf16 v[112:115], v[158:161], v[184:187], v[112:115]
	v_mfma_f32_16x16x32_bf16 v[100:103], v[144:147], v[192:195], v[100:103]
	v_lshl_add_u64 v[216:217], s[30:31], 0, v[132:133]
	v_mfma_f32_16x16x32_bf16 v[96:99], v[158:161], v[192:195], v[96:99]
	v_mfma_f32_16x16x32_bf16 v[84:87], v[144:147], v[200:203], v[84:87]
	v_mfma_f32_16x16x32_bf16 v[80:83], v[158:161], v[200:203], v[80:83]
	v_mfma_f32_16x16x32_bf16 v[68:71], v[144:147], v[208:211], v[68:71]
	v_lshl_add_u64 v[218:219], s[30:31], 0, v[128:129]
	v_mfma_f32_16x16x32_bf16 v[64:67], v[158:161], v[208:211], v[64:67]
	v_mfma_f32_16x16x32_bf16 v[116:119], v[154:157], v[188:191], v[116:119]
	v_mfma_f32_16x16x32_bf16 v[112:115], v[162:165], v[188:191], v[112:115]
	v_mfma_f32_16x16x32_bf16 v[100:103], v[154:157], v[196:199], v[100:103]
	v_lshl_add_u64 v[242:243], s[100:101], 0, v[132:133]
	v_mfma_f32_16x16x32_bf16 v[96:99], v[162:165], v[196:199], v[96:99]
	v_mfma_f32_16x16x32_bf16 v[84:87], v[154:157], v[204:207], v[84:87]
	v_mfma_f32_16x16x32_bf16 v[80:83], v[162:165], v[204:207], v[80:83]
	v_mfma_f32_16x16x32_bf16 v[68:71], v[154:157], v[212:215], v[68:71]
	v_mfma_f32_16x16x32_bf16 v[64:67], v[162:165], v[212:215], v[64:67]
	v_mfma_f32_16x16x32_bf16 v[124:127], v[168:171], v[184:187], v[124:127]
	v_mfma_f32_16x16x32_bf16 v[120:123], v[176:179], v[184:187], v[120:123]
	v_mfma_f32_16x16x32_bf16 v[108:111], v[168:171], v[192:195], v[108:111]
	v_lshl_add_u64 v[244:245], s[100:101], 0, v[128:129]
	v_mfma_f32_16x16x32_bf16 v[104:107], v[176:179], v[192:195], v[104:107]
	v_mfma_f32_16x16x32_bf16 v[92:95], v[168:171], v[200:203], v[92:95]
	v_mfma_f32_16x16x32_bf16 v[88:91], v[176:179], v[200:203], v[88:91]
	v_mfma_f32_16x16x32_bf16 v[76:79], v[168:171], v[208:211], v[76:79]
	v_lshl_add_u64 v[220:221], s[34:35], 0, v[134:135]
	v_mfma_f32_16x16x32_bf16 v[72:75], v[176:179], v[208:211], v[72:75]
	v_mfma_f32_16x16x32_bf16 v[124:127], v[172:175], v[188:191], v[124:127]
	v_mfma_f32_16x16x32_bf16 v[120:123], v[180:183], v[188:191], v[120:123]
	v_mfma_f32_16x16x32_bf16 v[108:111], v[172:175], v[196:199], v[108:111]
	v_lshl_add_u64 v[222:223], s[34:35], 0, v[130:131]
	v_mfma_f32_16x16x32_bf16 v[104:107], v[180:183], v[196:199], v[104:107]
	v_mfma_f32_16x16x32_bf16 v[92:95], v[172:175], v[204:207], v[92:95]
	v_mfma_f32_16x16x32_bf16 v[88:91], v[180:183], v[204:207], v[88:91]
	v_mfma_f32_16x16x32_bf16 v[76:79], v[172:175], v[212:215], v[76:79]
	v_mfma_f32_16x16x32_bf16 v[72:75], v[180:183], v[212:215], v[72:75]
	s_setprio 0
	s_barrier
	s_add_i32 s4, s41, s47
	s_mov_b32 m0, s4
	ds_read_b128 v[184:187], v151 offset:16384
	ds_read_b128 v[188:191], v151 offset:17408
	ds_read_b128 v[192:195], v151 offset:18432
	ds_read_b128 v[196:199], v151 offset:19456
	ds_read_b128 v[200:203], v151 offset:20480
	ds_read_b128 v[204:207], v151 offset:21504
	ds_read_b128 v[208:211], v151 offset:22528
	ds_read_b128 v[212:215], v151 offset:23552
	global_load_lds_dwordx4 v[216:217], off
	s_add_i32 m0, s4, 0x2000
	s_add_i32 s59, s44, s47
	global_load_lds_dwordx4 v[218:219], off
	s_mov_b32 m0, s59
	s_nop 0
	global_load_lds_dwordx4 v[242:243], off
	s_add_i32 m0, s59, 0x2000
	s_nop 0
	global_load_lds_dwordx4 v[244:245], off
	s_mov_b32 m0, s27
	s_nop 0
	global_load_lds_dwordx4 v[220:221], off
	s_mov_b32 m0, s33
	s_nop 0
	global_load_lds_dwordx4 v[222:223], off
	s_waitcnt vmcnt(8)
	s_waitcnt lgkmcnt(0)
	s_barrier
; #define PG8_STAGE(bufoff, gbase, voff) do { _Pragma("unroll") for (int _i = 0; _i < 2; ++_i) \
;         __builtin_amdgcn_global_load_lds((const unsigned*)((const char*)(gbase) + (voff)[_i]), (PG8_LAS unsigned*)(lds + (bufoff) + ldsw + _i * 8192), 16, 0, 0); } while (0)
; #define PG8_LDA(dst, b, h) do { _Pragma("unroll") for (int m = 0; m < 4; ++m) _Pragma("unroll") for (int k = 0; k < 2; ++k) dst[m][k] = *(const PG8_LAS bf16x8*)(lds + PG8_SA(b, h) + aoff + m * 2048 + k * 1024); } while (0)
; #define PG8_LDB(dst, b, h) do { _Pragma("unroll") for (int n = 0; n < 2; ++n) _Pragma("unroll") for (int k = 0; k < 2; ++k) dst[n][k] = *(const PG8_LAS bf16x8*)(lds + PG8_SB(b, h) + boff + n * 2048 + k * 1024); } while (0)
; #define PG8_MMA(ai, bj, At, Bt) do { __builtin_amdgcn_s_setprio(1); _Pragma("unroll") for (int m = 0; m < 4; ++m) _Pragma("unroll") for (int n = 0; n < 2; ++n) _Pragma("unroll") for (int k = 0; k < 2; ++k) \
;         acc[ai][bj][m][n] = __builtin_amdgcn_mfma_f32_16x16x32_bf16(Bt[n][k], At[m][k], acc[ai][bj][m][n], 0, 0, 0); __builtin_amdgcn_s_setprio(0); } while (0)
; #define PG8_WAIT_V(n) asm volatile("s_waitcnt vmcnt(" #n ")" ::: "memory")
; #define PG8_WAIT_L(n) asm volatile("s_waitcnt lgkmcnt(" #n ")" ::: "memory")
; #define PG8_BAR __builtin_amdgcn_s_barrier()
; #define PG8_SCHED __builtin_amdgcn_sched_barrier(0)
; template <class Epi, class Sched, bool ALIGN_EPI = false, bool SP2 = false>
; __device__ __forceinline__ void gemm_phase(PG8_LAS unsigned char* lds, const Gemm g, const Sched& S, const Epi& E) {
;     ...
;             PG8_WAIT_V(8); PG8_WAIT_L(0); PG8_BAR; PG8_MMA(1, 0, At, B0); PG8_MMA(1, 1, At, B1); PG8_BAR; PG8_SCHED;
;             PG8_LDB(B0, 1, 0); PG8_LDB(B1, 1, 1); PG8_SCHED; PG8_LDA(At, 1, 0); PG8_STAGE(PG8_SA(0, 1), a2 + hstepA, voffA);
	s_setprio 1
	v_mfma_f32_16x16x32_bf16 v[52:55], v[144:147], v[184:187], v[52:55]
	v_mfma_f32_16x16x32_bf16 v[48:51], v[158:161], v[184:187], v[48:51]
	v_mfma_f32_16x16x32_bf16 v[36:39], v[144:147], v[192:195], v[36:39]
	v_mfma_f32_16x16x32_bf16 v[32:35], v[158:161], v[192:195], v[32:35]
	v_mfma_f32_16x16x32_bf16 v[20:23], v[144:147], v[200:203], v[20:23]
	v_mfma_f32_16x16x32_bf16 v[16:19], v[158:161], v[200:203], v[16:19]
	v_mfma_f32_16x16x32_bf16 v[8:11], v[144:147], v[208:211], v[8:11]
	v_mfma_f32_16x16x32_bf16 v[4:7], v[158:161], v[208:211], v[4:7]
	v_mfma_f32_16x16x32_bf16 v[52:55], v[154:157], v[188:191], v[52:55]
	v_mfma_f32_16x16x32_bf16 v[48:51], v[162:165], v[188:191], v[48:51]
	v_mfma_f32_16x16x32_bf16 v[36:39], v[154:157], v[196:199], v[36:39]
	v_mfma_f32_16x16x32_bf16 v[32:35], v[162:165], v[196:199], v[32:35]
	v_mfma_f32_16x16x32_bf16 v[20:23], v[154:157], v[204:207], v[20:23]
	v_mfma_f32_16x16x32_bf16 v[16:19], v[162:165], v[204:207], v[16:19]
	v_mfma_f32_16x16x32_bf16 v[8:11], v[154:157], v[212:215], v[8:11]
	v_mfma_f32_16x16x32_bf16 v[4:7], v[162:165], v[212:215], v[4:7]
	v_mfma_f32_16x16x32_bf16 v[60:63], v[168:171], v[184:187], v[60:63]
	v_mfma_f32_16x16x32_bf16 v[56:59], v[176:179], v[184:187], v[56:59]
	v_mfma_f32_16x16x32_bf16 v[44:47], v[168:171], v[192:195], v[44:47]
	v_mfma_f32_16x16x32_bf16 v[40:43], v[176:179], v[192:195], v[40:43]
	v_mfma_f32_16x16x32_bf16 v[28:31], v[168:171], v[200:203], v[28:31]
	v_mfma_f32_16x16x32_bf16 v[24:27], v[176:179], v[200:203], v[24:27]
	v_mfma_f32_16x16x32_bf16 v[12:15], v[168:171], v[208:211], v[12:15]
	v_mfma_f32_16x16x32_bf16 v[0:3], v[176:179], v[208:211], v[0:3]
	v_mfma_f32_16x16x32_bf16 v[60:63], v[172:175], v[188:191], v[60:63]
	v_mfma_f32_16x16x32_bf16 v[56:59], v[180:183], v[188:191], v[56:59]
	v_mfma_f32_16x16x32_bf16 v[44:47], v[172:175], v[196:199], v[44:47]
	v_mfma_f32_16x16x32_bf16 v[40:43], v[180:183], v[196:199], v[40:43]
	v_mfma_f32_16x16x32_bf16 v[28:31], v[172:175], v[204:207], v[28:31]
	v_mfma_f32_16x16x32_bf16 v[24:27], v[180:183], v[204:207], v[24:27]
	v_mfma_f32_16x16x32_bf16 v[12:15], v[172:175], v[212:215], v[12:15]
	v_mfma_f32_16x16x32_bf16 v[0:3], v[180:183], v[212:215], v[0:3]
	s_setprio 0
	s_barrier
	s_add_i32 s59, 0, 0x18000
	v_add_u32_e32 v153, s59, v148
	s_add_i32 s60, 0, 0x1c000
	ds_read_b128 v[144:147], v153
	ds_read_b128 v[154:157], v153 offset:1024
	ds_read_b128 v[158:161], v153 offset:2048
	ds_read_b128 v[162:165], v153 offset:3072
	v_add_u32_e32 v153, s60, v148
	ds_read_b128 v[168:171], v153
	ds_read_b128 v[172:175], v153 offset:1024
	ds_read_b128 v[176:179], v153 offset:2048
	ds_read_b128 v[180:183], v153 offset:3072
	s_add_u32 s4, s34, 0x80000
	s_addc_u32 s5, s35, 0
	s_mov_b32 m0, s36
	v_lshl_add_u64 v[224:225], s[4:5], 0, v[134:135]
	ds_read_b128 v[184:187], v151 offset:32768
	ds_read_b128 v[188:191], v151 offset:33792
	ds_read_b128 v[192:195], v151 offset:34816
	ds_read_b128 v[196:199], v151 offset:35840
	ds_read_b128 v[200:203], v151 offset:36864
	ds_read_b128 v[204:207], v151 offset:37888
	ds_read_b128 v[208:211], v151 offset:38912
	ds_read_b128 v[212:215], v151 offset:39936
	global_load_lds_dwordx4 v[224:225], off
	v_lshl_add_u64 v[224:225], s[4:5], 0, v[130:131]
	s_mov_b32 m0, s37
	s_nop 0
	global_load_lds_dwordx4 v[224:225], off
	s_waitcnt vmcnt(8)
	s_waitcnt lgkmcnt(0)
	s_barrier
; #define PG8_STAGE(bufoff, gbase, voff) do { _Pragma("unroll") for (int _i = 0; _i < 2; ++_i) \
;         __builtin_amdgcn_global_load_lds((const unsigned*)((const char*)(gbase) + (voff)[_i]), (PG8_LAS unsigned*)(lds + (bufoff) + ldsw + _i * 8192), 16, 0, 0); } while (0)
; #define PG8_LDA(dst, b, h) do { _Pragma("unroll") for (int m = 0; m < 4; ++m) _Pragma("unroll") for (int k = 0; k < 2; ++k) dst[m][k] = *(const PG8_LAS bf16x8*)(lds + PG8_SA(b, h) + aoff + m * 2048 + k * 1024); } while (0)
; #define PG8_MMA(ai, bj, At, Bt) do { __builtin_amdgcn_s_setprio(1); _Pragma("unroll") for (int m = 0; m < 4; ++m) _Pragma("unroll") for (int n = 0; n < 2; ++n) _Pragma("unroll") for (int k = 0; k < 2; ++k) \
;         acc[ai][bj][m][n] = __builtin_amdgcn_mfma_f32_16x16x32_bf16(Bt[n][k], At[m][k], acc[ai][bj][m][n], 0, 0, 0); __builtin_amdgcn_s_setprio(0); } while (0)
; #define PG8_WAIT_V(n) asm volatile("s_waitcnt vmcnt(" #n ")" ::: "memory")
; #define PG8_WAIT_L(n) asm volatile("s_waitcnt lgkmcnt(" #n ")" ::: "memory")
; #define PG8_BAR __builtin_amdgcn_s_barrier()
; #define PG8_SCHED __builtin_amdgcn_sched_barrier(0)
; template <class Epi, class Sched, bool ALIGN_EPI = false, bool SP2 = false>
; __device__ __forceinline__ void gemm_phase(PG8_LAS unsigned char* lds, const Gemm g, const Sched& S, const Epi& E) {
;     ...
;             PG8_WAIT_V(8); PG8_WAIT_L(0); PG8_BAR; PG8_MMA(0, 0, At, B0); PG8_MMA(0, 1, At, B1); PG8_BAR; PG8_SCHED;
;             PG8_LDA(At, 1, 1); PG8_STAGE(PG8_SB(1, 0), b3, voffB); PG8_STAGE(PG8_SB(1, 1), b3 + hstepB, voffB); PG8_STAGE(PG8_SA(1, 0), a3, voffA);
;             PG8_WAIT_V(8); PG8_WAIT_L(0); PG8_BAR; PG8_MMA(1, 0, At, B0); PG8_MMA(1, 1, At, B1); PG8_BAR; PG8_SCHED;
	s_setprio 1
	v_mfma_f32_16x16x32_bf16 v[116:119], v[144:147], v[184:187], v[116:119]
	s_add_u32 s100, s30, 0x80080
	s_addc_u32 s101, s31, 0
	v_mfma_f32_16x16x32_bf16 v[112:115], v[158:161], v[184:187], v[112:115]
	v_mfma_f32_16x16x32_bf16 v[100:103], v[144:147], v[192:195], v[100:103]
	v_lshl_add_u64 v[216:217], v[216:217], 0, s[14:15]
	v_mfma_f32_16x16x32_bf16 v[96:99], v[158:161], v[192:195], v[96:99]
	v_mfma_f32_16x16x32_bf16 v[84:87], v[144:147], v[200:203], v[84:87]
	v_mfma_f32_16x16x32_bf16 v[80:83], v[158:161], v[200:203], v[80:83]
	v_mfma_f32_16x16x32_bf16 v[68:71], v[144:147], v[208:211], v[68:71]
	v_lshl_add_u64 v[218:219], v[218:219], 0, s[14:15]
	v_mfma_f32_16x16x32_bf16 v[64:67], v[158:161], v[208:211], v[64:67]
	v_mfma_f32_16x16x32_bf16 v[116:119], v[154:157], v[188:191], v[116:119]
	v_mfma_f32_16x16x32_bf16 v[112:115], v[162:165], v[188:191], v[112:115]
	v_mfma_f32_16x16x32_bf16 v[100:103], v[154:157], v[196:199], v[100:103]
	v_lshl_add_u64 v[242:243], s[100:101], 0, v[132:133]
	v_mfma_f32_16x16x32_bf16 v[96:99], v[162:165], v[196:199], v[96:99]
	v_mfma_f32_16x16x32_bf16 v[84:87], v[154:157], v[204:207], v[84:87]
	v_mfma_f32_16x16x32_bf16 v[80:83], v[162:165], v[204:207], v[80:83]
	v_mfma_f32_16x16x32_bf16 v[68:71], v[154:157], v[212:215], v[68:71]
	v_mfma_f32_16x16x32_bf16 v[64:67], v[162:165], v[212:215], v[64:67]
	v_mfma_f32_16x16x32_bf16 v[124:127], v[168:171], v[184:187], v[124:127]
	v_mfma_f32_16x16x32_bf16 v[120:123], v[176:179], v[184:187], v[120:123]
	v_mfma_f32_16x16x32_bf16 v[108:111], v[168:171], v[192:195], v[108:111]
	v_lshl_add_u64 v[244:245], s[100:101], 0, v[128:129]
	v_mfma_f32_16x16x32_bf16 v[104:107], v[176:179], v[192:195], v[104:107]
	v_mfma_f32_16x16x32_bf16 v[92:95], v[168:171], v[200:203], v[92:95]
	v_mfma_f32_16x16x32_bf16 v[88:91], v[176:179], v[200:203], v[88:91]
	v_mfma_f32_16x16x32_bf16 v[76:79], v[168:171], v[208:211], v[76:79]
	v_lshl_add_u64 v[220:221], v[220:221], 0, s[14:15]
	v_mfma_f32_16x16x32_bf16 v[72:75], v[176:179], v[208:211], v[72:75]
	v_mfma_f32_16x16x32_bf16 v[124:127], v[172:175], v[188:191], v[124:127]
	v_mfma_f32_16x16x32_bf16 v[120:123], v[180:183], v[188:191], v[120:123]
	v_mfma_f32_16x16x32_bf16 v[108:111], v[172:175], v[196:199], v[108:111]
	v_lshl_add_u64 v[222:223], v[222:223], 0, s[14:15]
	v_mfma_f32_16x16x32_bf16 v[104:107], v[180:183], v[196:199], v[104:107]
	v_mfma_f32_16x16x32_bf16 v[92:95], v[172:175], v[204:207], v[92:95]
	v_mfma_f32_16x16x32_bf16 v[88:91], v[180:183], v[204:207], v[88:91]
	v_mfma_f32_16x16x32_bf16 v[76:79], v[172:175], v[212:215], v[76:79]
	v_mfma_f32_16x16x32_bf16 v[72:75], v[180:183], v[212:215], v[72:75]
	s_setprio 0
	s_barrier
	s_add_i32 s4, s59, s47
	s_mov_b32 m0, s4
	ds_read_b128 v[184:187], v151 offset:49152
	ds_read_b128 v[188:191], v151 offset:50176
	ds_read_b128 v[192:195], v151 offset:51200
	ds_read_b128 v[196:199], v151 offset:52224
	ds_read_b128 v[200:203], v151 offset:53248
	ds_read_b128 v[204:207], v151 offset:54272
	ds_read_b128 v[208:211], v151 offset:55296
	ds_read_b128 v[212:215], v151 offset:56320
	global_load_lds_dwordx4 v[216:217], off
	s_add_i32 m0, s4, 0x2000
	s_add_i32 s30, s60, s47
	global_load_lds_dwordx4 v[218:219], off
	s_mov_b32 m0, s30
	s_nop 0
	global_load_lds_dwordx4 v[242:243], off
	s_add_i32 m0, s30, 0x2000
	s_nop 0
	global_load_lds_dwordx4 v[244:245], off
	s_mov_b32 m0, s39
	s_nop 0
	global_load_lds_dwordx4 v[220:221], off
	s_mov_b32 m0, s40
	s_nop 0
	global_load_lds_dwordx4 v[222:223], off
	s_waitcnt vmcnt(8)
	s_waitcnt lgkmcnt(0)
	s_barrier
	s_setprio 1
	v_mfma_f32_16x16x32_bf16 v[52:55], v[144:147], v[184:187], v[52:55]
	v_mfma_f32_16x16x32_bf16 v[48:51], v[158:161], v[184:187], v[48:51]
	v_mfma_f32_16x16x32_bf16 v[36:39], v[144:147], v[192:195], v[36:39]
	v_mfma_f32_16x16x32_bf16 v[32:35], v[158:161], v[192:195], v[32:35]
	v_mfma_f32_16x16x32_bf16 v[20:23], v[144:147], v[200:203], v[20:23]
	v_mfma_f32_16x16x32_bf16 v[16:19], v[158:161], v[200:203], v[16:19]
	v_mfma_f32_16x16x32_bf16 v[8:11], v[144:147], v[208:211], v[8:11]
	v_mfma_f32_16x16x32_bf16 v[4:7], v[158:161], v[208:211], v[4:7]
	v_mfma_f32_16x16x32_bf16 v[52:55], v[154:157], v[188:191], v[52:55]
	v_mfma_f32_16x16x32_bf16 v[48:51], v[162:165], v[188:191], v[48:51]
	v_mfma_f32_16x16x32_bf16 v[36:39], v[154:157], v[196:199], v[36:39]
	v_mfma_f32_16x16x32_bf16 v[32:35], v[162:165], v[196:199], v[32:35]
	v_mfma_f32_16x16x32_bf16 v[20:23], v[154:157], v[204:207], v[20:23]
	v_mfma_f32_16x16x32_bf16 v[16:19], v[162:165], v[204:207], v[16:19]
	v_mfma_f32_16x16x32_bf16 v[8:11], v[154:157], v[212:215], v[8:11]
	v_mfma_f32_16x16x32_bf16 v[4:7], v[162:165], v[212:215], v[4:7]
	v_mfma_f32_16x16x32_bf16 v[60:63], v[168:171], v[184:187], v[60:63]
	v_mfma_f32_16x16x32_bf16 v[56:59], v[176:179], v[184:187], v[56:59]
	v_mfma_f32_16x16x32_bf16 v[44:47], v[168:171], v[192:195], v[44:47]
	v_mfma_f32_16x16x32_bf16 v[40:43], v[176:179], v[192:195], v[40:43]
	v_mfma_f32_16x16x32_bf16 v[28:31], v[168:171], v[200:203], v[28:31]
	v_mfma_f32_16x16x32_bf16 v[24:27], v[176:179], v[200:203], v[24:27]
	v_mfma_f32_16x16x32_bf16 v[12:15], v[168:171], v[208:211], v[12:15]
	v_mfma_f32_16x16x32_bf16 v[0:3], v[176:179], v[208:211], v[0:3]
	v_mfma_f32_16x16x32_bf16 v[60:63], v[172:175], v[188:191], v[60:63]
	v_mfma_f32_16x16x32_bf16 v[56:59], v[180:183], v[188:191], v[56:59]
	v_mfma_f32_16x16x32_bf16 v[44:47], v[172:175], v[196:199], v[44:47]
	v_mfma_f32_16x16x32_bf16 v[40:43], v[180:183], v[196:199], v[40:43]
	v_mfma_f32_16x16x32_bf16 v[28:31], v[172:175], v[204:207], v[28:31]
	v_mfma_f32_16x16x32_bf16 v[24:27], v[180:183], v[204:207], v[24:27]
	v_mfma_f32_16x16x32_bf16 v[12:15], v[172:175], v[212:215], v[12:15]
	v_mfma_f32_16x16x32_bf16 v[0:3], v[180:183], v[212:215], v[0:3]
	s_setprio 0
	s_barrier
	s_add_i32 s58, s58, 2
	s_add_u32 s28, s28, 0x100
	s_addc_u32 s29, s29, 0
	s_add_u32 s56, s56, 0x100
	s_addc_u32 s57, s57, 0
	s_cmp_gt_u32 s58, 29
	s_cbranch_scc0 .LBB0_1287
	s_and_b64 vcc, exec, s[48:49]
	s_cbranch_vccz .LBB0_1290
	s_barrier

; __global__ void __launch_bounds__(NTHR, 2) fwd_megakernel(Args a_by_value) {
	.amdhsa_kernel _Z14fwd_megakernel4Args
		.amdhsa_group_segment_fixed_size 0
		.amdhsa_private_segment_fixed_size 0
		.amdhsa_kernarg_size 408
		.amdhsa_user_sgpr_count 2
		.amdhsa_user_sgpr_dispatch_ptr 0
		.amdhsa_user_sgpr_queue_ptr 0
		.amdhsa_user_sgpr_kernarg_segment_ptr 1
		.amdhsa_user_sgpr_dispatch_id 0
		.amdhsa_user_sgpr_kernarg_preload_length 0
		.amdhsa_user_sgpr_kernarg_preload_offset 0
		.amdhsa_user_sgpr_private_segment_size 0
		.amdhsa_uses_dynamic_stack 0
		.amdhsa_enable_private_segment 0
		.amdhsa_system_sgpr_workgroup_id_x 1
		.amdhsa_system_sgpr_workgroup_id_y 0
		.amdhsa_system_sgpr_workgroup_id_z 0
		.amdhsa_system_sgpr_workgroup_info 0
		.amdhsa_system_vgpr_workitem_id 2
		.amdhsa_next_free_vgpr 251
		.amdhsa_next_free_sgpr 102
		.amdhsa_accum_offset 252
		.amdhsa_reserve_vcc 1
		.amdhsa_float_round_mode_32 0
		.amdhsa_float_round_mode_16_64 0
		.amdhsa_float_denorm_mode_32 3
		.amdhsa_float_denorm_mode_16_64 3
		.amdhsa_dx10_clamp 1
		.amdhsa_ieee_mode 1
		.amdhsa_fp16_overflow 0
		.amdhsa_tg_split 0
		.amdhsa_exception_fp_ieee_invalid_op 0
		.amdhsa_exception_fp_denorm_src 0
		.amdhsa_exception_fp_ieee_div_zero 0
		.amdhsa_exception_fp_ieee_overflow 0
		.amdhsa_exception_fp_ieee_underflow 0
		.amdhsa_exception_fp_ieee_inexact 0
		.amdhsa_exception_int_div_zero 0
	.end_amdhsa_kernel

; __global__ void __launch_bounds__(NTHR, 2) fwd_megakernel(Args a_by_value) {
amdhsa.kernels:
  - .agpr_count:     0
    .args:
      - .offset:         0
        .size:           152
        .value_kind:     by_value
      - .offset:         152
        .size:           4
        .value_kind:     hidden_block_count_x
      - .offset:         156
        .size:           4
        .value_kind:     hidden_block_count_y
      - .offset:         160
        .size:           4
        .value_kind:     hidden_block_count_z
      - .offset:         164
        .size:           2
        .value_kind:     hidden_group_size_x
      - .offset:         166
        .size:           2
        .value_kind:     hidden_group_size_y
      - .offset:         168
        .size:           2
        .value_kind:     hidden_group_size_z
      - .offset:         170
        .size:           2
        .value_kind:     hidden_remainder_x
      - .offset:         172
        .size:           2
        .value_kind:     hidden_remainder_y
      - .offset:         174
        .size:           2
        .value_kind:     hidden_remainder_z
      - .offset:         192
        .size:           8
        .value_kind:     hidden_global_offset_x
      - .offset:         200
        .size:           8
        .value_kind:     hidden_global_offset_y
      - .offset:         208
        .size:           8
        .value_kind:     hidden_global_offset_z
      - .offset:         216
        .size:           2
        .value_kind:     hidden_grid_dims
      - .offset:         240
        .size:           8
        .value_kind:     hidden_multigrid_sync_arg
      - .offset:         272
        .size:           4
        .value_kind:     hidden_dynamic_lds_size
    .group_segment_fixed_size: 0
    .kernarg_segment_align: 8
    .kernarg_segment_size: 408
    .language:       OpenCL C
    .language_version:
      - 2
      - 0
    .max_flat_workgroup_size: 512
    .name:           _Z14fwd_megakernel4Args
    .private_segment_fixed_size: 0
    .sgpr_count:     108
    .sgpr_spill_count: 16
    .symbol:         _Z14fwd_megakernel4Args.kd
    .uniform_work_group_size: 1
    .uses_dynamic_stack: false
    .vgpr_count:     251
    .vgpr_spill_count: 0
    .wavefront_size: 64
